# speedup vs baseline: 1.0224x; 1.0069x over previous
; __device__ __forceinline__ void scan_quarter(LAS unsigned char* lds, const ScanConst& C, int m0, int T, int h, int quarter, const float* shift_prev  , const float* S0p  , float* Sout, const float* cWg, const float* cWu, const float* cWd, bf16* cWGU, bf16* cWD, int& conv_next, int conv_stride, int wa ...
;     ...
;     const int rl = lane >> 4, part = lane & 15, srow = 4 * (wave & 3) + rl, vrow = quarter * 16 + srow;
;     const int pw = wave & 3, ti = lane >> 3, cg = lane & 7, c0 = h * HD + cg * 8;
;     float S[4] = {0.f, 0.f, 0.f, 0.f};
;     float mu_r[8], mu_k[8], mu_v[8], kkc[8], kac[8];
;     u32x4 Lr, Lk, Lv, Lr0, Lk0, Lv0, Le, La;
;     f32x4 Fp[6];
;     if (scanner) { if (S0p) { const f32x4 a = *(const f32x4*)(S0p + vrow * HD + part * 4); S[0] = a[0]; S[1] = a[1]; S[2] = a[2]; S[3] = a[3]; } }
;     else {
; #pragma unroll
;         for (int q = 0; q < 2; ++q) { const f32x4 a = *(const f32x4*)(C.mu + c0 + 4 * q), b = *(const f32x4*)(C.mu + RW + c0 + 4 * q), c = *(const f32x4*)(C.mu + 2 * RW + c0 + 4 * q), d = *(const f32x4*)(C.k_k + c0 + 4 * q), e = *(const f32x4*)(C.k_a + c0 + 4 * q);
; #pragma unroll
;             for (int j = 0; j < 4; ++j) { mu_r[4 * q + j] = a[j]; mu_k[4 * q + j] = b[j]; mu_v[4 * q + j] = c[j]; kkc[4 * q + j] = d[j]; kac[4 * q + j] = e[j]; } }
;         if (shift_prev) {
; #pragma unroll
;             for (int q = 0; q < 2; ++q) { Fp[q] = *(const f32x4*)(shift_prev + c0 + 4 * q); Fp[2 + q] = *(const f32x4*)(shift_prev + RW + c0 + 4 * q); Fp[4 + q] = *(const f32x4*)(shift_prev + 2 * RW + c0 + 4 * q); }
;         } else {
; #pragma unroll
;             for (int q = 0; q < 6; ++q) Fp[q] = (f32x4){0.f, 0.f, 0.f, 0.f};
;         }
.LBB0_761:
	s_lshl_b32 s10, s97, 6
	s_and_b32 s10, s10, 0x3c0
	s_bfe_u32 s9, s97, 0x40004
	s_andn2_b64 vcc, exec, s[6:7]
	v_or_b32_e32 v2, s10, v141
	s_cbranch_vccnz .LBB0_765
	v_lshlrev_b32_e32 v4, 2, v2
	global_load_dwordx4 v[26:29], v4, s[64:65] offset:16
	global_load_dwordx4 v[50:53], v4, s[64:65]
	global_load_dwordx4 v[30:33], v4, s[66:67]
	global_load_dwordx4 v[14:17], v4, s[66:67] offset:16
	global_load_dwordx4 v[6:9], v4, s[68:69]
	global_load_dwordx4 v[10:13], v4, s[68:69] offset:16
	global_load_dwordx4 v[18:21], v4, s[24:25] offset:16
	global_load_dwordx4 v[22:25], v4, s[26:27] offset:16
	global_load_dwordx4 v[34:37], v4, s[24:25]
	global_load_dwordx4 v[46:49], v4, s[26:27]
	s_waitcnt lgkmcnt(0)
	s_cmp_lg_u64 s[28:29], 0
	v_mov_b32_e32 v41, 0
	v_mov_b32_e32 v57, 0
	v_mov_b32_e32 v56, 0
	v_mov_b32_e32 v55, 0
	v_mov_b32_e32 v54, 0
	v_mov_b32_e32 v45, 0
	v_mov_b32_e32 v44, 0
	v_mov_b32_e32 v43, 0
	v_mov_b32_e32 v42, 0
	v_mov_b32_e32 v69, 0
	v_mov_b32_e32 v68, 0
	v_mov_b32_e32 v67, 0
	v_mov_b32_e32 v66, 0
	v_mov_b32_e32 v73, 0
	v_mov_b32_e32 v72, 0
	v_mov_b32_e32 v71, 0
	v_mov_b32_e32 v70, 0
	v_mov_b32_e32 v61, 0
	v_mov_b32_e32 v60, 0
	v_mov_b32_e32 v59, 0
	v_mov_b32_e32 v58, 0
	v_mov_b32_e32 v65, 0
	v_mov_b32_e32 v64, 0
	v_mov_b32_e32 v63, 0
	v_mov_b32_e32 v62, 0
	s_cbranch_scc0 .LBB0_764
	s_mul_i32 s6, s9, 0x3480
	s_add_u32 s6, s28, s6
	s_addc_u32 s7, s29, 0
	v_lshl_add_u64 v[38:39], s[6:7], 0, v[4:5]
	global_load_dwordx4 v[62:65], v4, s[6:7]
	global_load_dwordx4 v[58:61], v4, s[6:7] offset:16
	s_movk_i32 s6, 0x1000
	s_mov_b64 s[28:29], 0x1000
	v_add_co_u32_e32 v42, vcc, s6, v38
	v_lshl_add_u64 v[54:55], v[38:39], 0, s[28:29]
	s_mov_b64 s[28:29], 0x2000
	v_addc_co_u32_e32 v43, vcc, 0, v39, vcc
	v_lshl_add_u64 v[56:57], v[38:39], 0, s[28:29]
	v_add_co_u32_e32 v38, vcc, 0x2000, v38
	s_nop 1
	v_addc_co_u32_e32 v39, vcc, 0, v39, vcc
	global_load_dwordx4 v[70:73], v[42:43], off
	s_nop 0
	global_load_dwordx4 v[42:45], v[38:39], off
	global_load_dwordx4 v[66:69], v[54:55], off offset:16
	s_nop 0
	global_load_dwordx4 v[54:57], v[56:57], off offset:16

; __device__ __forceinline__ void scan_quarter(LAS unsigned char* lds, const ScanConst& C, int m0, int T, int h, int quarter, const float* shift_prev  , const float* S0p  , float* Sout, const float* cWg, const float* cWu, const float* cWd, bf16* cWGU, bf16* cWD, int& conv_next, int conv_stride, int wa ...
;     ...
;     if (!scanner) { PREP_LOAD(0); PREP_FINISH(0, buf0); if (nch > 1) PREP_LOAD(1); }
.LBB0_765:
	s_andn2_b64 vcc, exec, s[52:53]
	s_cbranch_vccnz .LBB0_773
	s_lshl_b32 s9, s9, 6
	v_or_b32_e32 v3, s9, v142
	v_or_b32_e32 v86, 0x4000, v3
	v_mov_b64_e32 v[74:75], s[60:61]
	v_mad_u64_u32 v[74:75], s[6:7], v86, s85, v[74:75]
	v_lshlrev_b32_e32 v4, 1, v2
	v_lshl_add_u64 v[74:75], v[74:75], 0, v[4:5]
	v_add_co_u32_e32 v76, vcc, 0x1000, v74
	v_lshl_add_u64 v[2:3], v[74:75], 0, s[70:71]
	s_nop 0
	v_addc_co_u32_e32 v77, vcc, 0, v75, vcc
	v_add_co_u32_e32 v74, vcc, 0x2000, v74
	global_load_dwordx4 v[82:85], v[76:77], off offset:2048
	global_load_dwordx4 v[78:81], v[2:3], off offset:2048
	v_addc_co_u32_e32 v75, vcc, 0, v75, vcc
	global_load_dwordx4 v[74:77], v[74:75], off offset:2048
	s_and_saveexec_b64 s[6:7], s[4:5]
	s_cbranch_execz .LBB0_768
	v_add_co_u32_e32 v88, vcc, 0xffffd000, v2
	s_nop 1
	v_addc_co_u32_e32 v89, vcc, -1, v3, vcc
	v_add_co_u32_e32 v2, vcc, 0xffffe000, v2
	s_nop 1
	v_addc_co_u32_e32 v3, vcc, -1, v3, vcc
	global_load_dwordx4 v[102:105], v[88:89], off offset:-576
	global_load_dwordx4 v[98:101], v[2:3], off offset:-2624
	global_load_dwordx4 v[94:97], v[2:3], off offset:-576
